# grid barrier: L1 invalidate issued after the arrival atomic has returned (its in-order completion no longer delays that return)
# baseline (speedup 1.0000x reference)
.LBB0_69:
	s_or_b64 exec, exec, s[10:11]
	v_cvt_f32_u32_e32 v4, v2
	s_waitcnt vmcnt(0)
	v_readfirstlane_b32 s6, v3
	buffer_inv sc1
	v_sub_u32_e32 v3, 0, v2
	v_rcp_iflag_f32_e32 v4, v4
	v_add_u32_e32 v5, s6, v1
	v_mul_f32_e32 v4, 0x4f7ffffe, v4
	v_cvt_u32_f32_e32 v4, v4
	v_mul_lo_u32 v1, v3, v4
	v_mul_hi_u32 v1, v4, v1
	v_add_u32_e32 v1, v4, v1
	v_mul_hi_u32 v1, v5, v1
	v_mul_lo_u32 v3, v1, v2
	v_sub_u32_e32 v3, v5, v3
	v_add_u32_e32 v4, 1, v1
	v_cmp_ge_u32_e32 vcc, v3, v2
	s_nop 1
	v_cndmask_b32_e32 v1, v1, v4, vcc
	v_sub_u32_e32 v4, v3, v2
	v_cndmask_b32_e32 v3, v3, v4, vcc
	v_add_u32_e32 v4, 1, v1
	v_cmp_ge_u32_e32 vcc, v3, v2
	v_add_u32_e32 v3, 1, v5
	s_nop 0
	v_cndmask_b32_e32 v1, v1, v4, vcc
	v_mul_lo_u32 v4, v2, v1
	v_add_u32_e32 v2, v4, v2
	v_cmp_ne_u32_e32 vcc, v3, v2
	s_waitcnt lgkmcnt(0)
	v_add_u32_e32 v2, 1, v1
	v_mul_lo_u32 v2, v2, v0
	v_mov_b32_e32 v3, 0x3b000
	s_cbranch_vccnz .Lxb_poll_0
	buffer_wbl2 sc1
	s_waitcnt vmcnt(0)
	v_mov_b32_e32 v4, 1
	global_atomic_add v3, v4, s[30:31] offset:1024

.LBB0_411:
	s_or_b64 exec, exec, s[6:7]
	v_cvt_f32_u32_e32 v4, v2
	s_waitcnt vmcnt(0)
	v_readfirstlane_b32 s4, v3
	buffer_inv sc1
	v_sub_u32_e32 v3, 0, v2
	v_rcp_iflag_f32_e32 v4, v4
	v_add_u32_e32 v5, s4, v1
	v_mul_f32_e32 v4, 0x4f7ffffe, v4
	v_cvt_u32_f32_e32 v4, v4
	v_mul_lo_u32 v1, v3, v4
	v_mul_hi_u32 v1, v4, v1
	v_add_u32_e32 v1, v4, v1
	v_mul_hi_u32 v1, v5, v1
	v_mul_lo_u32 v3, v1, v2
	v_sub_u32_e32 v3, v5, v3
	v_add_u32_e32 v4, 1, v1
	v_cmp_ge_u32_e32 vcc, v3, v2
	s_nop 1
	v_cndmask_b32_e32 v1, v1, v4, vcc
	v_sub_u32_e32 v4, v3, v2
	v_cndmask_b32_e32 v3, v3, v4, vcc
	v_add_u32_e32 v4, 1, v1
	v_cmp_ge_u32_e32 vcc, v3, v2
	v_add_u32_e32 v3, 1, v5
	s_nop 0
	v_cndmask_b32_e32 v1, v1, v4, vcc
	v_mul_lo_u32 v4, v2, v1
	v_add_u32_e32 v2, v4, v2
	v_cmp_ne_u32_e32 vcc, v3, v2
	s_waitcnt lgkmcnt(0)
	v_add_u32_e32 v2, 1, v1
	v_mul_lo_u32 v2, v2, v0
	v_mov_b32_e32 v3, 0x3b000
	s_cbranch_vccnz .Lxb_poll_3
	buffer_wbl2 sc1
	s_waitcnt vmcnt(0)
	v_mov_b32_e32 v4, 1
	global_atomic_add v3, v4, s[30:31] offset:1024
